# v17 + stick-breaking step loop: O accumulator kept in v[2:33] (copy 0 renamed, 32 v_mov_b64 per 3 steps removed; copies only at loop entry/exit)
# speedup vs baseline: 1.0058x; 1.0002x over previous
; #define LAS __attribute__((address_space(3)))
; __device__ __forceinline__ float bf2f(short s) { return __uint_as_float(((unsigned)(unsigned short)s) << 16); }
; template <int MODE>
; __device__ __forceinline__ void attn_unit(LAS unsigned char* lds, const AttnArgs& A, int qb) {
;     ...
; #pragma unroll
;     for (int d0 = 0; d0 < 4; ++d0) qr[d0] = *(const bf16x8*)(A.Q + (size_t)row * A.ldq + d0 * 16 + hi * 8);
;     int i1 = -1, i2 = -1, i3 = -1; unsigned long long wmask = 0ull;
;     if (MODE == M_MOBA) {
;         const int own = qb;
;         LAS float* km = (LAS float*)(lds + KM_OFF);
;         {
;             float kp_[8][4];
; #pragma unroll
;             for (int k = 0; k < 8; ++k) { const int idx = tid + 512 * k; const bool ok = idx < own * 64; const float* p = A.kpart + (size_t)((ok ? idx : 0) >> 6) * 256 + (idx & 63);
;                 kp_[k][0] = p[0]; kp_[k][1] = p[64]; kp_[k][2] = p[128]; kp_[k][3] = p[192]; }
; #pragma unroll
;             for (int k = 0; k < 8; ++k) { const int idx = tid + 512 * k; if (idx < own * 64) km[idx] = ((kp_[k][0] + kp_[k][1]) + (kp_[k][2] + kp_[k][3])) * (1.0f / 256.0f); }
;         }
;         __syncthreads();
;         float qf[32];
; #pragma unroll
;         for (int d0 = 0; d0 < 4; ++d0)
; #pragma unroll
;             for (int e = 0; e < 8; ++e) qf[d0 * 8 + e] = bf2f(qr[d0][e]);
;         float v1 = -INFINITY, v2 = -INFINITY, v3 = -INFINITY;
; #pragma unroll 4
;         for (int j = 0; j < own; ++j) {
;             float g = 0.f;
; #pragma unroll
;             for (int d0 = 0; d0 < 4; ++d0) { const f32x4 a = *(const LAS f32x4*)(km + j * 64 + d0 * 16 + hi * 8), b = *(const LAS f32x4*)(km + j * 64 + d0 * 16 + hi * 8 + 4);
; template <int MODE> ...
;     ...
;         if (counter) {
;             if (threadIdx.x == 0) *slot = (int)__hip_atomic_fetch_add(counter, 1u, __ATOMIC_RELAXED, __HIP_MEMORY_SCOPE_AGENT);
;             __syncthreads(); idx = *slot - idx0; __syncthreads();
;             if (idx >= nunits) break;
;             if (idx < 0) continue;
;         } else { idx = (int)blockIdx.x; if (idx >= nunits) break; }
;         const int h = head_major ? (nheads - 1 - idx / 64) : (idx % nheads), qb = head_major ? (63 - idx % 64) : (63 - idx / nheads), hh = head0 + h;
;         att::AttnArgs a; a.Q = Q + hh * 64; a.ldq = ldq; a.K = K + hh * 64; a.V = V + hh * 64; a.ldkv = ldkv; a.O = O + hh * 64; a.ldo = ldo;
.LBB0_1162:
	s_or_b64 exec, exec, s[6:7]
	v_mov_b32_e32 v0, s95
	s_waitcnt lgkmcnt(0)
	s_barrier
	ds_read_b32 v0, v0
	s_mov_b64 s[6:7], -1
	s_waitcnt lgkmcnt(0)
	s_barrier
	v_cmp_lt_i32_e32 vcc, s62, v0
	v_readfirstlane_b32 s0, v0
	s_cbranch_vccnz .LBB0_1157
	s_cmp_lt_i32 s0, 0
	s_cbranch_scc1 .LBB0_1156
	s_lshl_b32 s1, s0, 6
	s_and_b32 s1, s1, 0x1c0
	v_writelane_b32 v255, s1, 45
	s_lshl_b32 s1, s1, 1
	v_readlane_b32 s2, v255, 37
	s_add_u32 s2, s2, s1
	v_readlane_b32 s3, v255, 38
	s_addc_u32 s3, s3, 0
	v_readlane_b32 s4, v255, 39
	s_add_u32 s10, s4, s1
	v_readlane_b32 s4, v255, 40
	s_addc_u32 s11, s4, 0
	v_readlane_b32 s4, v255, 41
	s_add_u32 s12, s4, s1
	v_readlane_b32 s1, v255, 42
	s_addc_u32 s13, s1, 0
	s_lshl_b32 s0, s0, 5
	v_mov_b32_e32 v0, v216
	s_and_b32 s16, s0, 0x1fff00
	s_sub_i32 s6, 0x3f00, s16
	s_waitcnt vmcnt(9)
	v_and_b32_e32 v130, 63, v0
	v_readfirstlane_b32 s1, v0
	s_ashr_i32 s4, s1, 6
	v_or_b32_e32 v2, s6, v130
	v_lshlrev_b32_e32 v6, 11, v2
	s_lshl_b32 s0, s4, 3
	v_or_b32_e32 v2, 0x60000, v6
	v_mov_b32_e32 v3, v1
	s_ashr_i32 s1, s0, 31
	s_lshl_b32 s5, s4, 5
	v_lshl_add_u64 v[4:5], s[10:11], 0, v[2:3]
	s_lshl_b64 s[14:15], s[0:1], 1
	v_lshl_add_u64 v[2:3], s[12:13], 0, v[2:3]
	v_and_b32_e32 v12, 31, v0
	s_add_i32 s5, s5, s6
	v_lshl_add_u64 v[2:3], v[2:3], 0, s[14:15]
	s_waitcnt vmcnt(8)
	v_or_b32_e32 v126, s5, v12
	v_lshl_add_u64 v[4:5], v[4:5], 0, s[14:15]
	global_load_dwordx4 v[70:73], v[2:3], off
	v_mov_b32_e32 v3, v1
	v_ashrrev_i32_e32 v127, 31, v126
	v_or_b32_e32 v2, 0x40000, v6
	global_load_dwordx4 v[66:69], v[4:5], off
	v_mov_b32_e32 v5, v1
	v_bfe_u32 v13, v0, 5, 1
	v_or_b32_e32 v4, 0x20000, v6
	v_lshlrev_b64 v[6:7], 11, v[126:127]
	v_lshl_add_u64 v[8:9], s[10:11], 0, v[2:3]
	v_mov_b32_e32 v123, v1
	v_lshlrev_b32_e32 v122, 4, v13
	v_lshl_add_u64 v[2:3], s[12:13], 0, v[2:3]
	v_lshl_add_u64 v[10:11], s[12:13], 0, v[4:5]
	v_lshl_add_u64 v[4:5], s[10:11], 0, v[4:5]
	v_lshl_add_u64 v[6:7], s[2:3], 0, v[6:7]
	v_lshl_add_u64 v[8:9], v[8:9], 0, s[14:15]
	v_lshl_add_u64 v[2:3], v[2:3], 0, s[14:15]
	v_lshl_add_u64 v[10:11], v[10:11], 0, s[14:15]
	v_lshl_add_u64 v[4:5], v[4:5], 0, s[14:15]
	v_lshl_add_u64 v[6:7], v[6:7], 0, v[122:123]
	global_load_dwordx4 v[90:93], v[8:9], off
	global_load_dwordx4 v[94:97], v[2:3], off
	global_load_dwordx4 v[102:105], v[10:11], off
	global_load_dwordx4 v[98:101], v[4:5], off
	global_load_dwordx4 v[74:77], v[6:7], off
	global_load_dwordx4 v[78:81], v[6:7], off offset:32
	global_load_dwordx4 v[82:85], v[6:7], off offset:64
	global_load_dwordx4 v[86:89], v[6:7], off offset:96
	s_lshl_b32 s0, s4, 10
	s_lshl_b32 s1, s4, 7
	s_add_i32 s0, s0, 0
	v_lshlrev_b32_e32 v123, 4, v130
	v_lshlrev_b32_e32 v131, 1, v130
	s_mul_i32 s7, s4, 0xfffffb84
	s_add_i32 s85, s0, s1
	v_add_u32_e32 v133, s0, v123
	v_add_u32_e32 v134, s85, v131
	s_add_i32 s85, s85, s7
	s_mul_i32 s0, s4, 0x3fc
	s_lshr_b32 s76, s6, 6
	s_add_i32 s84, s85, s0
	s_add_i32 s2, s76, 4
	s_or_b32 s68, s76, 2
	s_or_b32 s69, s5, 31
	s_add_i32 s79, s84, s1
	v_lshlrev_b32_e32 v3, 1, v0
	v_lshrrev_b32_e32 v4, 1, v0
	s_add_u32 s90, s10, s14
	v_and_b32_e32 v2, 19, v0
	v_and_b32_e32 v3, 8, v3
	v_and_b32_e32 v4, 4, v4
	s_addc_u32 s91, s11, s15
	v_mov_b32_e32 v48, v1
	v_mov_b32_e32 v49, v1
	v_mov_b32_e32 v108, v1
	v_mov_b32_e32 v109, v1
	v_mul_u32_u24_e32 v132, 0x90, v12
	v_or3_b32 v2, v3, v2, v4
	s_add_u32 s88, s12, s14
	v_mov_b32_e32 v34, v1
	v_mov_b32_e32 v35, v1
	v_mov_b32_e32 v36, v1
	v_mov_b32_e32 v37, v1
	v_mov_b32_e32 v38, v1
	v_mov_b32_e32 v39, v1
	v_mov_b32_e32 v40, v1
	v_mov_b32_e32 v41, v1
	v_mov_b32_e32 v42, v1
	v_mov_b32_e32 v43, v1
	v_mov_b32_e32 v44, v1
	v_mov_b32_e32 v45, v1
	v_mov_b32_e32 v46, v1
	v_mov_b32_e32 v47, v1
	v_mov_b32_e32 v106, v1
	v_mov_b32_e32 v107, v1
	v_mov_b64_e32 v[116:117], v[108:109]
	v_mov_b64_e32 v[112:113], v[108:109]
	v_mov_b64_e32 v[120:121], v[108:109]
	v_mov_b64_e32 v[64:65], v[48:49]
	s_mov_b32 s3, 8
	v_lshlrev_b32_e32 v0, 3, v13
	v_lshlrev_b64 v[124:125], 10, v[126:127]
	v_lshl_add_u32 v127, v2, 4, 0
	v_lshlrev_b32_e32 v135, 10, v13
	v_cmp_gt_u32_e64 s[6:7], 32, v130
	s_mov_b32 s0, 0
	v_cmp_eq_u32_e64 s[8:9], 0, v130
	v_add3_u32 v136, 0, v132, v122
	s_addc_u32 s89, s13, s15
	s_sub_i32 s1, 0x3fff, s16
	v_mov_b32_e32 v129, 0
	s_mov_b64 s[12:13], 0
	v_mov_b64_e32 v[114:115], v[106:107]
	v_mov_b64_e32 v[110:111], v[106:107]
	v_mov_b64_e32 v[118:119], v[106:107]
	s_mov_b32 s16, 0
	v_mov_b64_e32 v[62:63], v[46:47]
	v_mov_b64_e32 v[60:61], v[44:45]
	v_mov_b64_e32 v[58:59], v[42:43]
	v_mov_b64_e32 v[56:57], v[40:41]
	v_mov_b64_e32 v[54:55], v[38:39]
	v_mov_b64_e32 v[52:53], v[36:37]
	v_mov_b64_e32 v[50:51], v[34:35]
	s_waitcnt vmcnt(0)
	ds_write_b128 v133, v[66:69]
	ds_write_b16 v134, v70 offset:8192
	ds_write_b16_d16_hi v134, v70 offset:8336
	ds_write_b16 v134, v71 offset:8480
	ds_write_b16_d16_hi v134, v71 offset:8624
	ds_write_b16 v134, v72 offset:8768
	ds_write_b16_d16_hi v134, v72 offset:8912
	ds_write_b16 v134, v73 offset:9056
	ds_write_b16_d16_hi v134, v73 offset:9200
	s_waitcnt lgkmcnt(0)
	s_barrier
	v_mov_b64_e32 v[18:19], v[34:35]
	v_mov_b64_e32 v[20:21], v[36:37]
	v_mov_b64_e32 v[22:23], v[38:39]
	v_mov_b64_e32 v[24:25], v[40:41]
	v_mov_b64_e32 v[26:27], v[42:43]
	v_mov_b64_e32 v[28:29], v[44:45]
	v_mov_b64_e32 v[30:31], v[46:47]
	v_mov_b64_e32 v[32:33], v[48:49]
	v_mov_b64_e32 v[2:3], v[50:51]
	v_mov_b64_e32 v[4:5], v[52:53]
	v_mov_b64_e32 v[6:7], v[54:55]
	v_mov_b64_e32 v[8:9], v[56:57]
	v_mov_b64_e32 v[10:11], v[58:59]
	v_mov_b64_e32 v[12:13], v[60:61]
	v_mov_b64_e32 v[14:15], v[62:63]
	v_mov_b64_e32 v[16:17], v[64:65]
	s_cmp_ge_u32 s0, s2
	s_mov_b64 s[10:11], -1
	s_cbranch_scc0 .LBB0_1166

; #define LAS __attribute__((address_space(3)))
; #define LOADT(i, kreg, vreg, creg) do { const int k0_ = KEY0(i); kreg = *(const u32x4*)(A.K + (size_t)(k0_ + lane) * A.ldkv + wid * 8); vreg = *(const u32x4*)(A.V + (size_t)(k0_ + lane) * A.ldkv + wid * 8); \
;         if (MODE == M_FOX) { if (tid < 64) creg = A.cf[k0_ + tid] * LOG2E; } } while (0)
; #define PVS(s, pk) do { const bf16x8 a0_ = *(const LAS bf16x8*)(vb + (s) * 32), a1_ = *(const LAS bf16x8*)(vb + 32 * VT_STRIDE + (s) * 32); \
;             o0 = __builtin_amdgcn_mfma_f32_32x32x16_bf16(a0_, pk, o0, 0, 0, 0); o1 = __builtin_amdgcn_mfma_f32_32x32x16_bf16(a1_, pk, o1, 0, 0, 0); } while (0)
; #define PVS(s, pk) do { const bf16x8 a0_ = *(const LAS bf16x8*)(vb + (s) * 32), a1_ = *(const LAS bf16x8*)(vb + 32 * VT_STRIDE + (s) * 32); \
;             o0 = __builtin_amdgcn_mfma_f32_32x32x16_bf16(a0_, pk, o0, 0, 0, 0); o1 = __builtin_amdgcn_mfma_f32_32x32x16_bf16(a1_, pk, o1, 0, 0, 0); } while (0)
; #define PVS(s, pk) do { const bf16x8 a0_ = *(const LAS bf16x8*)(vb + (s) * 32), a1_ = *(const LAS bf16x8*)(vb + 32 * VT_STRIDE + (s) * 32); \
;             o0 = __builtin_amdgcn_mfma_f32_32x32x16_bf16(a0_, pk, o0, 0, 0, 0); o1 = __builtin_amdgcn_mfma_f32_32x32x16_bf16(a1_, pk, o1, 0, 0, 0); } while (0)
; #define PVS(s, pk) do { const bf16x8 a0_ = *(const LAS bf16x8*)(vb + (s) * 32), a1_ = *(const LAS bf16x8*)(vb + 32 * VT_STRIDE + (s) * 32); \
;             o0 = __builtin_amdgcn_mfma_f32_32x32x16_bf16(a0_, pk, o0, 0, 0, 0); o1 = __builtin_amdgcn_mfma_f32_32x32x16_bf16(a1_, pk, o1, 0, 0, 0); } while (0)
; template <int MODE>
; __device__ __forceinline__ void attn_unit(LAS unsigned char* lds, const AttnArgs& A, int qb) {
;     ...
;         { const int i = i0 + 0; if (i >= NT) break;
;         const int key0 = KEY0(i);
;         if (i + 3 < NT) LOADT(i + 3, k1, v1, c1);
;         LAS unsigned char* buf = lds + 0 * BUF_BYTES;
;         bool active;
;         if (MODE == M_XA) active = true;
;         else if (MODE == M_MOBA) active = (i < 4) ? (key0 <= w0 + 31) : (((wmask >> ((i - 4) >> 2)) & 1ull) != 0ull);
;         else active = key0 <= w0 + 31;
;     ...
;         if (prev_active) {
;             const LAS unsigned char* vb = lds + prevbuf + KB_BYTES + r32 * VT_STRIDE + hi * 16;
;     ...
;             PVS(0, pkP0); PVS(1, pkP1); PVS(2, pkP2); PVS(3, pkP3);
;     ...
;         }
.LBB0_1166:
	s_add_i32 s80, s0, 3
	s_cmp_lt_u32 s80, s2
	s_cselect_b64 s[96:97], -1, 0
	s_cmp_ge_u32 s80, s2
	v_add_u32_e32 v50, s1, v130
	v_add_u32_e32 v50, 0xffffff01, v50
	v_ashrrev_i32_e32 v51, 31, v50
	v_lshlrev_b64 v[50:51], 11, v[50:51]
	v_lshl_add_u64 v[52:53], s[88:89], 0, v[50:51]
	v_lshl_add_u64 v[50:51], s[90:91], 0, v[50:51]
	global_load_dwordx4 v[66:69], v[50:51], off
	global_load_dwordx4 v[70:73], v[52:53], off
.LBB0_1168:
	s_sub_i32 s10, s1, 63
	s_cmp_le_i32 s10, s69
	v_cndmask_b32_e64 v50, 0, 1, s[12:13]
	s_cselect_b64 s[92:93], -1, 0
	s_cmp_gt_i32 s10, s69
	s_mov_b64 s[14:15], -1
	v_cmp_ne_u32_e64 s[10:11], 1, v50
	s_cbranch_scc0 .LBB0_1172
	s_and_b64 vcc, exec, s[10:11]
	s_cbranch_vccnz .LBB0_1171
	v_add_u32_e32 v128, s16, v136
	ds_read_b128 v[138:141], v128 offset:8192
	s_waitcnt lgkmcnt(0)
	v_mfma_f32_32x32x16_bf16 v[2:17], v[138:141], v[118:121], v[2:17]
	ds_read_b128 v[138:141], v128 offset:12800
	s_waitcnt lgkmcnt(0)
	v_mfma_f32_32x32x16_bf16 v[18:33], v[138:141], v[118:121], v[18:33]
	ds_read_b128 v[138:141], v128 offset:8224
	s_waitcnt lgkmcnt(0)
	v_mfma_f32_32x32x16_bf16 v[2:17], v[138:141], v[110:113], v[2:17]
	ds_read_b128 v[138:141], v128 offset:12832
	s_waitcnt lgkmcnt(0)
	v_mfma_f32_32x32x16_bf16 v[18:33], v[138:141], v[110:113], v[18:33]
	ds_read_b128 v[138:141], v128 offset:8256
	s_waitcnt lgkmcnt(0)
	v_mfma_f32_32x32x16_bf16 v[2:17], v[138:141], v[114:117], v[2:17]
	ds_read_b128 v[138:141], v128 offset:12864
	s_waitcnt lgkmcnt(0)
	v_mfma_f32_32x32x16_bf16 v[18:33], v[138:141], v[114:117], v[18:33]
	ds_read_b128 v[138:141], v128 offset:8288
	s_waitcnt lgkmcnt(0)
	v_mfma_f32_32x32x16_bf16 v[2:17], v[138:141], v[106:109], v[2:17]
	ds_read_b128 v[138:141], v128 offset:12896
	s_waitcnt lgkmcnt(0)
	v_mfma_f32_32x32x16_bf16 v[18:33], v[138:141], v[106:109], v[18:33]

; #define LAS __attribute__((address_space(3)))
; #define PVS(s, pk) do { const bf16x8 a0_ = *(const LAS bf16x8*)(vb + (s) * 32), a1_ = *(const LAS bf16x8*)(vb + 32 * VT_STRIDE + (s) * 32); \
;             o0 = __builtin_amdgcn_mfma_f32_32x32x16_bf16(a0_, pk, o0, 0, 0, 0); o1 = __builtin_amdgcn_mfma_f32_32x32x16_bf16(a1_, pk, o1, 0, 0, 0); } while (0)
; template <int MODE>
; __device__ __forceinline__ void attn_unit(LAS unsigned char* lds, const AttnArgs& A, int qb) {
;     ...
;             f32x16 p0, p1;
; #pragma unroll
;             for (int r = 0; r < 16; ++r) { p0[r] = 0.f; p1[r] = 0.f; }
;             LAS unsigned char* kb = buf + kperm * 16 + hi * 1024;
; #pragma unroll
;             for (int d0 = 0; d0 < 4; ++d0) {
;                 const bf16x8 kf0 = *(const LAS bf16x8*)(kb + d0 * 2048), kf1 = *(const LAS bf16x8*)(kb + d0 * 2048 + 512);
;                 p0 = __builtin_amdgcn_mfma_f32_32x32x16_bf16(kf0, qr[d0], p0, 0, 0, 0);
;                 p1 = __builtin_amdgcn_mfma_f32_32x32x16_bf16(kf1, qr[d0], p1, 0, 0, 0);
;             }
;         if (prev_active) {
;             const LAS unsigned char* vb = lds + prevbuf + KB_BYTES + r32 * VT_STRIDE + hi * 16;
;     ...
;             PVS(0, pkP0); PVS(1, pkP1); PVS(2, pkP2); PVS(3, pkP3);
;     ...
;         }
;             const int kl = key0 + 8 * hi;
;             if (MODE == M_SB) {
;                 const bool nm = key0 + 63 >= w0;
;                 f32x16 L0, L1; float gt[4];
; #pragma unroll
;                 for (int g = 0; g < 4; ++g) gt[g] = 0.f;
; #pragma unroll
;                 for (int r = 0; r < 16; ++r) {
;                     { const float z2 = p0[r] * C2; p0[r] = z2; float l1 = -(fmaxf(z2, 0.f) + __builtin_amdgcn_logf(1.0f + __builtin_amdgcn_exp2f(-fabsf(z2))));
;                       if (nm && !(kl + 16 * (r >> 3) + (r & 7) < row)) l1 = 0.f; L0[r] = l1; gt[r >> 3] += l1; }
;                     { const float z2 = p1[r] * C2; p1[r] = z2; float l1 = -(fmaxf(z2, 0.f) + __builtin_amdgcn_logf(1.0f + __builtin_amdgcn_exp2f(-fabsf(z2))));
;                       if (nm && !(kl + 32 + 16 * (r >> 3) + (r & 7) < row)) l1 = 0.f; L1[r] = l1; gt[2 + (r >> 3)] += l1; }
;                 }
.LBB0_1172:
	s_andn2_b64 vcc, exec, s[14:15]
	s_cbranch_vccnz .LBB0_1176
	v_add_u32_e32 v128, v127, v135
	s_nop 4
	ds_read_b128 v[50:53], v128
	ds_read_b128 v[138:141], v128 offset:2048
	s_and_b64 vcc, exec, s[10:11]
	s_waitcnt lgkmcnt(1)
	v_mfma_f32_32x32x16_bf16 v[34:49], v[50:53], v[74:77], 0
	ds_read_b128 v[50:53], v128 offset:512
	s_waitcnt lgkmcnt(1)
	v_mfma_f32_32x32x16_bf16 v[34:49], v[138:141], v[78:81], v[34:49]
	ds_read_b128 v[138:141], v128 offset:2560
	s_waitcnt lgkmcnt(1)
	v_mfma_f32_32x32x16_bf16 v[50:65], v[50:53], v[74:77], 0
	s_waitcnt lgkmcnt(0)
	v_mfma_f32_32x32x16_bf16 v[50:65], v[138:141], v[78:81], v[50:65]
	ds_read_b128 v[138:141], v128 offset:4096
	s_waitcnt lgkmcnt(0)
	v_mfma_f32_32x32x16_bf16 v[34:49], v[138:141], v[82:85], v[34:49]
	ds_read_b128 v[138:141], v128 offset:4608
	s_waitcnt lgkmcnt(0)
	v_mfma_f32_32x32x16_bf16 v[50:65], v[138:141], v[82:85], v[50:65]
	ds_read_b128 v[138:141], v128 offset:6144
	s_waitcnt lgkmcnt(0)
	v_mfma_f32_32x32x16_bf16 v[34:49], v[138:141], v[86:89], v[34:49]
	ds_read_b128 v[138:141], v128 offset:6656
	s_waitcnt lgkmcnt(0)
	v_mfma_f32_32x32x16_bf16 v[50:65], v[138:141], v[86:89], v[50:65]
	s_cbranch_vccnz .LBB0_1175
	v_add_u32_e32 v128, s16, v136
	ds_read_b128 v[138:141], v128 offset:8192
	s_waitcnt lgkmcnt(0)
	v_mfma_f32_32x32x16_bf16 v[2:17], v[138:141], v[118:121], v[2:17]
	ds_read_b128 v[138:141], v128 offset:12800
	s_waitcnt lgkmcnt(0)
	v_mfma_f32_32x32x16_bf16 v[18:33], v[138:141], v[118:121], v[18:33]
	ds_read_b128 v[118:121], v128 offset:8224
	s_waitcnt lgkmcnt(0)
	v_mfma_f32_32x32x16_bf16 v[2:17], v[118:121], v[110:113], v[2:17]
	ds_read_b128 v[118:121], v128 offset:12832
	s_waitcnt lgkmcnt(0)
	v_mfma_f32_32x32x16_bf16 v[18:33], v[118:121], v[110:113], v[18:33]
	ds_read_b128 v[110:113], v128 offset:8256
	s_waitcnt lgkmcnt(0)
	v_mfma_f32_32x32x16_bf16 v[2:17], v[110:113], v[114:117], v[2:17]
	ds_read_b128 v[110:113], v128 offset:12864
	s_waitcnt lgkmcnt(0)
	v_mfma_f32_32x32x16_bf16 v[18:33], v[110:113], v[114:117], v[18:33]
	ds_read_b128 v[110:113], v128 offset:8288
	s_waitcnt lgkmcnt(0)
	v_mfma_f32_32x32x16_bf16 v[2:17], v[110:113], v[106:109], v[2:17]
	ds_read_b128 v[110:113], v128 offset:12896
	s_waitcnt lgkmcnt(0)
	v_mfma_f32_32x32x16_bf16 v[18:33], v[110:113], v[106:109], v[18:33]
.LBB0_1175:
	s_nop 10
	v_mul_f32_e32 v107, 0x3e38aa3b, v50
	v_exp_f32_e64 v108, -|v107|
	v_add_u32_e32 v109, s1, v0
	v_subrev_u32_e32 v106, 63, v109
	v_cmp_lt_i32_e64 s[10:11], v106, v126
	v_add_f32_e32 v106, 1.0, v108
	v_mul_f32_e32 v108, 0x3e38aa3b, v35
	v_log_f32_e32 v106, v106
	v_exp_f32_e64 v112, -|v108|
	v_subrev_u32_e32 v111, 31, v109
	v_max_f32_e32 v107, 0, v107
	v_add_f32_e32 v110, v107, v106
	v_cmp_lt_i32_e32 vcc, v111, v126
	v_add_f32_e32 v107, 1.0, v112
	v_mul_f32_e32 v111, 0x3e38aa3b, v51
	v_log_f32_e32 v107, v107
	v_exp_f32_e64 v113, -|v111|
	v_max_f32_e32 v108, 0, v108
	v_mul_f32_e32 v115, 0x3e38aa3b, v37
	v_add_f32_e32 v112, v108, v107
	v_add_f32_e32 v107, 1.0, v113
	v_log_f32_e32 v107, v107
	v_subrev_u32_e32 v108, 62, v109
	v_cmp_lt_i32_e64 s[14:15], v108, v126
	v_max_f32_e32 v108, 0, v111
	v_add_f32_e32 v107, v108, v107
	v_subrev_u32_e32 v108, 30, v109
	v_cmp_lt_i32_e64 s[12:13], v108, v126
	v_mul_f32_e32 v108, 0x3e38aa3b, v52
	v_exp_f32_e64 v113, -|v108|
	v_exp_f32_e64 v116, -|v115|
	v_subrev_u32_e32 v114, 61, v109
	v_max_f32_e32 v108, 0, v108
	v_add_f32_e32 v113, 1.0, v113
	v_log_f32_e32 v113, v113
	v_cmp_lt_i32_e64 s[18:19], v114, v126
	v_max_f32_e32 v115, 0, v115
	v_subrev_u32_e32 v121, 58, v109
	v_add_f32_e32 v114, v108, v113
	v_subrev_u32_e32 v108, 29, v109
	v_cmp_lt_i32_e64 s[16:17], v108, v126
	v_add_f32_e32 v108, 1.0, v116
	v_mul_f32_e32 v116, 0x3e38aa3b, v53
	v_log_f32_e32 v108, v108
	v_exp_f32_e64 v117, -|v116|
	v_max_f32_e32 v116, 0, v116
	s_cmp_lt_i32 s1, s5
	v_add_f32_e32 v115, v115, v108
	v_add_f32_e32 v108, 1.0, v117
	v_log_f32_e32 v108, v108
	v_subrev_u32_e32 v117, 60, v109
	v_cmp_lt_i32_e64 s[20:21], v117, v126
	v_cmp_lt_i32_e64 s[30:31], v121, v126
	v_add_f32_e32 v117, v116, v108
	v_subrev_u32_e32 v108, 28, v109
	v_cmp_lt_i32_e64 s[22:23], v108, v126
	v_mul_f32_e32 v108, 0x3e38aa3b, v54
	v_exp_f32_e64 v118, -|v108|
	v_max_f32_e32 v108, 0, v108
	s_cselect_b64 s[86:87], -1, 0
	v_sub_f32_e32 v106, 0, v110
	v_add_f32_e32 v118, 1.0, v118
	v_log_f32_e32 v118, v118
	s_or_b64 vcc, s[86:87], vcc
	s_or_b64 s[12:13], s[86:87], s[12:13]
	v_cndmask_b32_e32 v106, 0, v106, vcc
	v_add_f32_e32 v118, v108, v118
	v_subrev_u32_e32 v108, 27, v109
	v_cmp_lt_i32_e64 s[24:25], v108, v126
	v_mul_f32_e32 v108, 0x3e38aa3b, v55
	v_exp_f32_e64 v120, -|v108|
	v_max_f32_e32 v108, 0, v108
	v_cndmask_b32_e64 v111, 0, -v107, s[12:13]
	s_or_b64 s[16:17], s[86:87], s[16:17]
	v_add_f32_e32 v120, 1.0, v120
	v_log_f32_e32 v120, v120
	v_add_f32_e32 v106, v111, v106
	v_cndmask_b32_e64 v113, 0, -v114, s[16:17]
	s_or_b64 s[22:23], s[86:87], s[22:23]
	v_add_f32_e32 v137, v108, v120
	v_mul_f32_e32 v120, 0x3e38aa3b, v40
	v_exp_f32_e64 v121, -|v120|
	v_subrev_u32_e32 v108, 26, v109
	v_cmp_lt_i32_e64 s[26:27], v108, v126
	v_add_f32_e32 v106, v113, v106
	v_add_f32_e32 v108, 1.0, v121
	v_mul_f32_e32 v121, 0x3e38aa3b, v56
	v_cndmask_b32_e64 v116, 0, -v117, s[22:23]
	v_subrev_u32_e32 v119, 59, v109
	s_or_b64 s[24:25], s[86:87], s[24:25]
	v_log_f32_e32 v108, v108
	v_exp_f32_e64 v128, -|v121|
	v_add_f32_e32 v106, v116, v106
	v_cmp_lt_i32_e64 s[28:29], v119, v126
	v_cndmask_b32_e64 v119, 0, -v118, s[24:25]
	s_or_b64 s[34:35], s[86:87], s[26:27]
	v_add_f32_e32 v106, v119, v106
	v_cndmask_b32_e64 v142, 0, -v137, s[34:35]
	v_add_f32_e32 v138, v142, v106
	v_max_f32_e32 v106, 0, v120
	v_add_f32_e32 v143, v106, v108
; template <int MODE>
; __device__ __forceinline__ void attn_unit(LAS unsigned char* lds, const AttnArgs& A, int qb) {
;     ...
;                 for (int r = 0; r < 16; ++r) {
;                     { const float z2 = p0[r] * C2; p0[r] = z2; float l1 = -(fmaxf(z2, 0.f) + __builtin_amdgcn_logf(1.0f + __builtin_amdgcn_exp2f(-fabsf(z2))));
;                       if (nm && !(kl + 16 * (r >> 3) + (r & 7) < row)) l1 = 0.f; L0[r] = l1; gt[r >> 3] += l1; }
;                     { const float z2 = p1[r] * C2; p1[r] = z2; float l1 = -(fmaxf(z2, 0.f) + __builtin_amdgcn_logf(1.0f + __builtin_amdgcn_exp2f(-fabsf(z2))));
;                       if (nm && !(kl + 32 + 16 * (r >> 3) + (r & 7) < row)) l1 = 0.f; L1[r] = l1; gt[2 + (r >> 3)] += l1; }
;                 }
;                 float pt[4], after[4]; float run = 0.f;
; #pragma unroll
;                 for (int g = 0; g < 4; ++g) pt[g] = __shfl_xor(gt[g], 32);
; #pragma unroll
;                 for (int g = 3; g >= 0; --g) { after[g] = run + (hi ? 0.f : pt[g]); run += gt[g] + pt[g]; }
; #pragma unroll
;     ...
;                     float s0 = T + after[g8], s1 = T + after[2 + g8];
; #pragma unroll
;                     for (int e = 7; e >= 0; --e) { const int r = 8 * g8 + e;
;                         { const bool valid = !nm || (kl + 16 * g8 + e < row); const float a = valid ? __builtin_amdgcn_exp2f(p0[r] + L0[r] + s0) : 0.f; s0 += L0[r]; p0[r] = a; }
	v_add_f32_e32 v106, 1.0, v128
	v_log_f32_e32 v106, v106
	v_subrev_u32_e32 v108, 57, v109
	v_cmp_lt_i32_e64 s[36:37], v108, v126
	v_max_f32_e32 v108, 0, v121
	v_add_f32_e32 v144, v108, v106
	v_subrev_u32_e32 v106, 25, v109
	v_cmp_lt_i32_e64 s[26:27], v106, v126
	v_mul_f32_e32 v106, 0x3e38aa3b, v41
	v_exp_f32_e64 v41, -|v106|
	v_mul_f32_e32 v121, 0x3e38aa3b, v57
	v_exp_f32_e64 v128, -|v121|
	v_max_f32_e32 v108, 0, v106
	v_add_f32_e32 v41, 1.0, v41
	v_log_f32_e32 v41, v41
	s_or_b64 s[38:39], s[86:87], s[26:27]
	v_cndmask_b32_e64 v145, 0, -v144, s[38:39]
	v_add_f32_e32 v120, v145, v138
	v_add_f32_e32 v41, v108, v41
	v_subrev_u32_e32 v108, 56, v109
	v_cmp_lt_i32_e64 s[26:27], v108, v126
	v_add_f32_e32 v108, 1.0, v128
	v_log_f32_e32 v128, v108
	s_or_b64 s[26:27], s[86:87], s[26:27]
	v_cndmask_b32_e64 v108, 0, -v41, s[26:27]
	v_max_f32_e32 v41, 0, v121
	v_subrev_u32_e32 v121, 24, v109
	v_cmp_lt_i32_e64 s[40:41], v121, v126
	v_mul_f32_e32 v121, 0x3e38aa3b, v58
	v_add_f32_e32 v41, v41, v128
	v_exp_f32_e64 v128, -|v121|
	s_or_b64 s[40:41], s[86:87], s[40:41]
	v_cndmask_b32_e64 v146, 0, -v41, s[40:41]
	v_add_f32_e32 v138, v146, v120
	v_add_f32_e32 v120, 1.0, v128
	v_log_f32_e32 v120, v120
	v_max_f32_e32 v121, 0, v121
	v_mul_f32_e32 v139, 0x3e38aa3b, v59
	v_exp_f32_e64 v140, -|v139|
	v_add_f32_e32 v147, v121, v120
	v_mul_f32_e32 v120, 0x3e38aa3b, v43
	v_exp_f32_e64 v121, -|v120|
	v_max_f32_e32 v120, 0, v120
	v_max_f32_e32 v139, 0, v139
	v_subrev_u32_e32 v153, 43, v109
	v_add_f32_e32 v121, 1.0, v121
	v_log_f32_e32 v121, v121
	v_cmp_lt_i32_e64 s[60:61], v153, v126
	v_subrev_u32_e32 v155, 42, v109
	v_cmp_lt_i32_e64 s[64:65], v155, v126
	v_add_f32_e32 v121, v120, v121
	v_add_f32_e32 v120, 1.0, v140
	v_log_f32_e32 v120, v120
	v_subrev_u32_e32 v140, 46, v109
	v_cmp_lt_i32_e64 s[48:49], v140, v126
	v_subrev_u32_e32 v140, 45, v109
	v_add_f32_e32 v148, v139, v120
	v_add_u32_e32 v120, -14, v109
	v_cmp_lt_i32_e64 s[46:47], v120, v126
	v_mul_f32_e32 v120, 0x3e38aa3b, v60
	v_exp_f32_e64 v139, -|v120|
	v_max_f32_e32 v120, 0, v120
	v_cmp_lt_i32_e64 s[52:53], v140, v126
	v_mul_f32_e32 v155, 0x3e38aa3b, v48
	v_add_f32_e32 v139, 1.0, v139
	v_log_f32_e32 v139, v139
	v_exp_f32_e64 v156, -|v155|
	v_max_f32_e32 v155, 0, v155
	v_mul_f32_e32 v159, 0x3e38aa3b, v65
	v_add_f32_e32 v150, v120, v139
	v_mul_f32_e32 v139, 0x3e38aa3b, v45
	v_exp_f32_e64 v140, -|v139|
	v_add_u32_e32 v120, -13, v109
	v_cmp_lt_i32_e64 s[50:51], v120, v126
	v_max_f32_e32 v139, 0, v139
	v_add_f32_e32 v120, 1.0, v140
	v_mul_f32_e32 v140, 0x3e38aa3b, v61
	v_log_f32_e32 v120, v120
	v_exp_f32_e64 v141, -|v140|
	v_subrev_u32_e32 v128, 47, v109
	v_exp_f32_e64 v160, -|v159|
	v_add_f32_e32 v152, v139, v120
	v_add_f32_e32 v120, 1.0, v141
	v_log_f32_e32 v120, v120
	v_subrev_u32_e32 v139, 44, v109
	v_cmp_lt_i32_e64 s[54:55], v139, v126
	v_max_f32_e32 v139, 0, v140
	v_add_f32_e32 v140, v139, v120
	v_add_u32_e32 v120, -12, v109
	v_cmp_lt_i32_e64 s[56:57], v120, v126
	v_mul_f32_e32 v120, 0x3e38aa3b, v62
	v_exp_f32_e64 v139, -|v120|
	v_max_f32_e32 v120, 0, v120
	v_cmp_lt_i32_e64 s[44:45], v128, v126
	v_add_u32_e32 v128, -15, v109
	v_add_f32_e32 v139, 1.0, v139
	v_log_f32_e32 v139, v139
	v_cmp_lt_i32_e64 s[42:43], v128, v126
	v_sub_f32_e32 v128, 0, v147
	s_or_b64 s[42:43], s[86:87], s[42:43]
	v_add_f32_e32 v153, v120, v139
	v_add_u32_e32 v120, -11, v109
	v_cmp_lt_i32_e64 s[58:59], v120, v126
	v_mul_f32_e32 v120, 0x3e38aa3b, v63
	v_exp_f32_e64 v139, -|v120|
	v_max_f32_e32 v120, 0, v120
	s_or_b64 s[46:47], s[86:87], s[46:47]
	v_cndmask_b32_e64 v128, 0, v128, s[42:43]
	v_add_f32_e32 v139, 1.0, v139
	v_log_f32_e32 v139, v139
	v_cndmask_b32_e64 v149, 0, -v148, s[46:47]
	s_or_b64 s[50:51], s[86:87], s[50:51]
	v_add_f32_e32 v160, 1.0, v160
	v_add_f32_e32 v139, v120, v139
	v_add_u32_e32 v120, -10, v109
	v_cmp_lt_i32_e64 s[62:63], v120, v126
	v_add_f32_e32 v120, 1.0, v156
	v_mul_f32_e32 v156, 0x3e38aa3b, v64
	v_log_f32_e32 v120, v120
	v_exp_f32_e64 v158, -|v156|
	v_max_f32_e32 v156, 0, v156
	s_or_b64 s[66:67], s[86:87], s[62:63]
	v_add_f32_e32 v155, v155, v120
	v_add_f32_e32 v120, 1.0, v158
	v_log_f32_e32 v120, v120
	v_add_f32_e32 v128, v149, v128
	v_cndmask_b32_e64 v151, 0, -v150, s[50:51]
	s_or_b64 s[56:57], s[86:87], s[56:57]
	v_add_f32_e32 v156, v156, v120
	v_add_u32_e32 v120, -9, v109
	v_cmp_lt_i32_e64 s[62:63], v120, v126
	v_mul_f32_e32 v120, 0x3e38aa3b, v49
	v_exp_f32_e64 v49, -|v120|
	v_log_f32_e32 v160, v160
	v_add_f32_e32 v128, v151, v128
	v_cndmask_b32_e64 v141, 0, -v140, s[56:57]
	v_add_f32_e32 v49, 1.0, v49
	v_log_f32_e32 v49, v49
	s_or_b64 s[58:59], s[86:87], s[58:59]
	v_max_f32_e32 v161, 0, v120
	v_add_f32_e32 v128, v141, v128
	v_cndmask_b32_e64 v154, 0, -v153, s[58:59]
	v_subrev_u32_e32 v158, 41, v109
	v_add_f32_e32 v49, v161, v49
	v_subrev_u32_e32 v161, 40, v109
	v_add_u32_e32 v109, -8, v109
	v_add_f32_e32 v128, v154, v128
	v_cndmask_b32_e64 v157, 0, -v139, s[66:67]
	s_or_b64 s[72:73], s[86:87], s[62:63]
	v_max_f32_e32 v159, 0, v159
	v_cmp_lt_i32_e64 s[62:63], v109, v126
	v_add_f32_e32 v128, v157, v128
	v_cmp_lt_i32_e64 s[70:71], v158, v126
	v_cndmask_b32_e64 v158, 0, -v156, s[72:73]
	v_add_f32_e32 v159, v159, v160
	s_or_b64 s[74:75], s[86:87], s[62:63]
	v_add_f32_e32 v128, v158, v128
	v_cndmask_b32_e64 v109, 0, -v159, s[74:75]
	v_and_b32_e32 v162, 64, v223
	v_add_f32_e32 v160, v109, v128
	v_xor_b32_e32 v128, 32, v223
	v_add_u32_e32 v162, 64, v162
	v_cmp_lt_i32_e64 s[62:63], v128, v162
	v_fma_f32 v65, v65, s78, -v159
	v_fma_f32 v64, v64, s78, -v156
	v_cndmask_b32_e64 v128, v223, v128, s[62:63]
	v_lshlrev_b32_e32 v162, 2, v128
	v_cmp_lt_i32_e64 s[62:63], v161, v126
	ds_bpermute_b32 v163, v162, v160
	s_or_b64 s[62:63], s[86:87], s[62:63]
	v_cndmask_b32_e64 v128, 0, -v49, s[62:63]
	ds_bpermute_b32 v49, v162, v138
	v_fma_f32 v63, v63, s78, -v139
	s_waitcnt lgkmcnt(1)
; template <int MODE>
; __device__ __forceinline__ void attn_unit(LAS unsigned char* lds, const AttnArgs& A, int qb) {
;     ...
;                 float pt[4], after[4]; float run = 0.f;
; #pragma unroll
;                 for (int g = 0; g < 4; ++g) pt[g] = __shfl_xor(gt[g], 32);
; #pragma unroll
;                 for (int g = 3; g >= 0; --g) { after[g] = run + (hi ? 0.f : pt[g]); run += gt[g] + pt[g]; }
; #pragma unroll
;     ...
;                     float s0 = T + after[g8], s1 = T + after[2 + g8];
; #pragma unroll
;                     for (int e = 7; e >= 0; --e) { const int r = 8 * g8 + e;
;                         { const bool valid = !nm || (kl + 16 * g8 + e < row); const float a = valid ? __builtin_amdgcn_exp2f(p0[r] + L0[r] + s0) : 0.f; s0 += L0[r]; p0[r] = a; }
;                         { const bool valid = !nm || (kl + 32 + 16 * g8 + e < row); const float a = valid ? __builtin_amdgcn_exp2f(p1[r] + L1[r] + s1) : 0.f; s1 += L1[r]; p1[r] = a; } }
	v_add_f32_e32 v161, 0, v163
	v_add_f32_e32 v160, v160, v163
	v_cndmask_b32_e64 v161, 0, v161, s[6:7]
	v_add_f32_e32 v160, 0, v160
	s_waitcnt lgkmcnt(0)
	v_cndmask_b32_e64 v163, 0, v49, s[6:7]
	v_add_f32_e32 v49, v138, v49
	v_add_f32_e32 v163, v163, v160
	v_add_f32_e32 v160, v49, v160
	v_add_f32_e32 v49, v129, v161
	v_add_f32_e32 v65, v65, v49
	v_add_f32_e32 v49, v109, v49
	v_add_f32_e32 v64, v64, v49
	v_add_f32_e32 v49, v158, v49
	v_exp_f32_e32 v109, v64
	v_add_f32_e32 v63, v63, v49
	v_mul_f32_e32 v64, 0x3e38aa3b, v46
	v_exp_f32_e32 v63, v63
	v_exp_f32_e64 v46, -|v64|
	v_exp_f32_e32 v65, v65
	s_or_b64 s[60:61], s[86:87], s[60:61]
	v_cndmask_b32_e64 v159, 0, v63, s[66:67]
	v_add_f32_e32 v63, 1.0, v46
	v_mul_f32_e32 v46, 0x3e38aa3b, v47
	v_cndmask_b32_e64 v156, 0, v65, s[74:75]
	v_exp_f32_e64 v65, -|v46|
	v_log_f32_e32 v63, v63
	v_add_f32_e32 v47, v157, v49
	v_max_f32_e32 v49, 0, v64
	v_add_f32_e32 v65, 1.0, v65
	v_log_f32_e32 v65, v65
	v_add_f32_e32 v63, v49, v63
	v_cndmask_b32_e64 v138, 0, -v63, s[60:61]
	v_max_f32_e32 v63, 0, v46
	s_or_b64 s[66:67], s[86:87], s[70:71]
	v_fma_f32 v62, v62, s78, -v153
	v_add_f32_e32 v63, v63, v65
	v_cndmask_b32_e64 v49, 0, -v155, s[66:67]
	s_or_b64 s[64:65], s[86:87], s[64:65]
	v_add_f32_e32 v62, v62, v47
	v_fmamk_f32 v65, v48, 0x3e38aa3b, v49
	v_cndmask_b32_e64 v48, 0, -v63, s[64:65]
	v_exp_f32_e32 v63, v62
	v_mul_f32_e32 v62, 0x3e38aa3b, v44
	v_exp_f32_e64 v44, -|v62|
	v_add_f32_e32 v47, v154, v47
	v_fma_f32 v61, v61, s78, -v140
	v_add_f32_e32 v61, v61, v47
	v_exp_f32_e32 v61, v61
	v_cndmask_b32_e64 v153, 0, v63, s[58:59]
	v_add_f32_e32 v63, 1.0, v44
	v_log_f32_e32 v63, v63
	v_cndmask_b32_e64 v154, 0, v61, s[56:57]
	v_max_f32_e32 v61, 0, v62
	s_or_b64 s[52:53], s[86:87], s[52:53]
	v_add_f32_e32 v61, v61, v63
	v_mul_f32_e32 v44, 0x3e38aa3b, v42
	v_cndmask_b32_e64 v140, 0, -v61, s[52:53]
	v_exp_f32_e64 v61, -|v44|
	v_add_f32_e32 v47, v141, v47
	v_fma_f32 v60, v60, s78, -v150
	v_add_f32_e32 v60, v60, v47
	v_exp_f32_e32 v60, v60
	v_add_f32_e32 v61, 1.0, v61
	v_log_f32_e32 v61, v61
	s_or_b64 s[44:45], s[86:87], s[44:45]
	v_cndmask_b32_e64 v150, 0, v60, s[50:51]
	v_max_f32_e32 v60, 0, v44
	v_add_f32_e32 v60, v60, v61
	v_cndmask_b32_e64 v60, 0, -v60, s[44:45]
	s_or_b64 s[48:49], s[86:87], s[48:49]
	v_add_f32_e32 v63, 0, v60
	v_cndmask_b32_e64 v61, 0, -v121, s[48:49]
	s_or_b64 s[54:55], s[86:87], s[54:55]
	v_add_f32_e32 v63, v61, v63
	v_cndmask_b32_e64 v141, 0, -v152, s[54:55]
	v_add_f32_e32 v63, v140, v63
	v_add_f32_e32 v63, v141, v63
	v_add_f32_e32 v63, v138, v63
	v_add_f32_e32 v63, v48, v63
	v_add_f32_e32 v63, v49, v63
	v_add_f32_e32 v63, v128, v63
	v_fmamk_f32 v42, v45, 0x3e38aa3b, v141
	ds_bpermute_b32 v45, v162, v63
	v_cndmask_b32_e64 v158, 0, v109, s[72:73]
	v_add_f32_e32 v109, v151, v47
	v_fma_f32 v59, v59, s78, -v148
	v_add_f32_e32 v59, v59, v109
	s_waitcnt lgkmcnt(0)
; template <int MODE>
; __device__ __forceinline__ void attn_unit(LAS unsigned char* lds, const AttnArgs& A, int qb) {
;     ...
;                     float s0 = T + after[g8], s1 = T + after[2 + g8];
; #pragma unroll
;                     for (int e = 7; e >= 0; --e) { const int r = 8 * g8 + e;
;                         { const bool valid = !nm || (kl + 16 * g8 + e < row); const float a = valid ? __builtin_amdgcn_exp2f(p0[r] + L0[r] + s0) : 0.f; s0 += L0[r]; p0[r] = a; }
;                         { const bool valid = !nm || (kl + 32 + 16 * g8 + e < row); const float a = valid ? __builtin_amdgcn_exp2f(p1[r] + L1[r] + s1) : 0.f; s1 += L1[r]; p1[r] = a; } }
;                 }
;                 T += run;
;     ...
;             pkP0 = pack8(p0, 0); pkP1 = pack8(p0, 8); pkP2 = pack8(p1, 0); pkP3 = pack8(p1, 8);
	v_cndmask_b32_e64 v47, 0, v45, s[6:7]
	v_add_f32_e32 v121, v47, v160
	v_pk_add_f32 v[120:121], v[120:121], v[128:129]
	v_exp_f32_e32 v59, v59
	v_add_f32_e32 v47, v120, v121
	v_exp_f32_e32 v47, v47
	v_mov_b32_e32 v139, v48
	v_cndmask_b32_e64 v148, 0, v59, s[46:47]
	v_add_f32_e32 v59, v63, v45
	v_cndmask_b32_e64 v151, 0, v47, s[62:63]
	v_add_f32_e32 v47, v128, v121
	v_add_f32_e32 v120, v59, v160
	v_add_f32_e32 v59, v65, v47
	v_pk_add_f32 v[46:47], v[46:47], v[48:49]
	v_exp_f32_e32 v59, v59
	v_add_f32_e32 v63, v46, v47
	v_mov_b32_e32 v65, v47
	v_exp_f32_e32 v45, v63
	v_pk_add_f32 v[64:65], v[64:65], v[138:139]
	v_fma_f32 v58, v58, s78, -v147
	v_add_f32_e32 v63, v64, v65
	v_exp_f32_e32 v64, v63
	v_add_f32_e32 v63, v138, v65
	v_add_f32_e32 v65, v42, v63
	v_pk_add_f32 v[62:63], v[62:63], v[140:141]
	v_cndmask_b32_e64 v46, 0, v45, s[64:65]
	v_add_f32_e32 v45, v140, v63
	v_cndmask_b32_e64 v42, 0, v59, s[66:67]
	v_add_f32_e32 v59, v62, v63
	v_fmamk_f32 v62, v43, 0x3e38aa3b, v61
	v_pk_add_f32 v[60:61], v[44:45], v[60:61]
	v_exp_f32_e32 v59, v59
	v_add_f32_e32 v60, v60, v61
	v_add_f32_e32 v61, v149, v109
	v_add_f32_e32 v58, v58, v61
	v_exp_f32_e32 v58, v58
	v_exp_f32_e32 v60, v60
	v_fma_f32 v57, v57, s78, -v41
	v_fma_f32 v56, v56, s78, -v144
	v_cndmask_b32_e64 v49, 0, v58, s[42:43]
	v_add_f32_e32 v58, v129, v163
	v_add_f32_e32 v57, v57, v58
	v_add_f32_e32 v58, v146, v58
	v_add_f32_e32 v62, v62, v45
	v_cndmask_b32_e64 v45, 0, v60, s[44:45]
	v_add_f32_e32 v56, v56, v58
	v_add_f32_e32 v60, v145, v58
	v_fma_f32 v55, v55, s78, -v137
	v_cndmask_b32_e64 v43, 0, v59, s[52:53]
	v_exp_f32_e32 v59, v56
	v_add_f32_e32 v55, v55, v60
	v_mul_f32_e32 v56, 0x3e38aa3b, v38
	v_exp_f32_e32 v55, v55
	v_exp_f32_e64 v58, -|v56|
	v_exp_f32_e32 v57, v57
	v_exp_f32_e32 v62, v62
	v_cndmask_b32_e64 v137, 0, v55, s[34:35]
	v_add_f32_e32 v55, 1.0, v58
	v_mul_f32_e32 v58, 0x3e38aa3b, v39
	v_cndmask_b32_e64 v41, 0, v57, s[40:41]
	v_exp_f32_e64 v57, -|v58|
	v_log_f32_e32 v55, v55
	v_cndmask_b32_e64 v128, 0, v59, s[38:39]
	v_add_f32_e32 v59, v142, v60
	v_add_f32_e32 v57, 1.0, v57
	v_log_f32_e32 v57, v57
	v_max_f32_e32 v60, 0, v56
	v_add_f32_e32 v55, v60, v55
	s_or_b64 s[28:29], s[86:87], s[28:29]
	v_cndmask_b32_e64 v60, 0, -v55, s[28:29]
	v_max_f32_e32 v55, 0, v58
	v_fma_f32 v54, v54, s78, -v118
	v_add_f32_e32 v55, v55, v57
	s_or_b64 s[30:31], s[86:87], s[30:31]
	v_add_f32_e32 v54, v54, v59
	v_cndmask_b32_e64 v44, 0, v62, s[48:49]
	v_cndmask_b32_e64 v62, 0, -v55, s[30:31]
	v_exp_f32_e32 v55, v54
	v_mul_f32_e32 v54, 0x3e38aa3b, v36
	v_cndmask_b32_e64 v47, 0, v64, s[60:61]
	v_exp_f32_e64 v64, -|v54|
	s_or_b64 s[34:35], s[86:87], s[36:37]
	v_add_f32_e32 v59, v119, v59
	v_fma_f32 v53, v53, s78, -v117
	v_cndmask_b32_e64 v63, 0, -v143, s[34:35]
	v_add_f32_e32 v53, v53, v59
	v_fmamk_f32 v57, v40, 0x3e38aa3b, v63
	v_exp_f32_e32 v53, v53
	v_cndmask_b32_e64 v40, 0, v55, s[24:25]
	v_add_f32_e32 v55, 1.0, v64
	v_log_f32_e32 v55, v55
	v_cndmask_b32_e64 v117, 0, v53, s[22:23]
	v_max_f32_e32 v53, 0, v54
	s_or_b64 s[18:19], s[86:87], s[18:19]
	v_add_f32_e32 v53, v53, v55
	v_mul_f32_e32 v36, 0x3e38aa3b, v34
	v_cndmask_b32_e64 v64, 0, -v53, s[18:19]
	v_exp_f32_e64 v53, -|v36|
	v_exp_f32_e32 v65, v65
	v_add_f32_e32 v59, v116, v59
	v_fma_f32 v52, v52, s78, -v114
	v_add_f32_e32 v53, 1.0, v53
	v_log_f32_e32 v53, v53
	v_add_f32_e32 v52, v52, v59
	v_exp_f32_e32 v55, v52
	v_max_f32_e32 v52, 0, v36
	s_or_b64 s[20:21], s[86:87], s[20:21]
	v_add_f32_e32 v52, v52, v53
	s_or_b64 s[10:11], s[86:87], s[10:11]
	v_cndmask_b32_e64 v48, 0, v65, s[54:55]
	v_cndmask_b32_e64 v65, 0, -v115, s[20:21]
	v_cndmask_b32_e64 v52, 0, -v52, s[10:11]
	s_or_b64 s[14:15], s[86:87], s[14:15]
	v_fmamk_f32 v34, v37, 0x3e38aa3b, v65
	v_add_f32_e32 v37, 0, v52
	v_cndmask_b32_e64 v53, 0, -v112, s[14:15]
	v_add_f32_e32 v37, v53, v37
	v_add_f32_e32 v37, v64, v37
	v_add_f32_e32 v37, v65, v37
	v_add_f32_e32 v37, v60, v37
	v_add_f32_e32 v37, v62, v37
	v_add_f32_e32 v37, v63, v37
	v_add_f32_e32 v37, v108, v37
	ds_bpermute_b32 v112, v162, v37
	v_add_f32_e32 v113, v113, v59
	v_mov_b32_e32 v109, v129
	v_fma_f32 v51, v51, s78, -v107
	v_mov_b32_e32 v61, v62
	s_waitcnt lgkmcnt(0)
	v_cndmask_b32_e64 v59, 0, v112, s[6:7]
	v_add_f32_e32 v107, v59, v120
	v_pk_add_f32 v[38:39], v[106:107], v[108:109]
	v_add_f32_e32 v106, v37, v112
	v_add_f32_e32 v59, v38, v39
	v_exp_f32_e32 v59, v59
	v_cndmask_b32_e64 v38, 0, v55, s[16:17]
	v_fma_f32 v50, v50, s78, -v110
	v_add_f32_e32 v51, v51, v113
	v_cndmask_b32_e64 v107, 0, v59, s[26:27]
	v_add_f32_e32 v59, v108, v39
	v_add_f32_e32 v55, v57, v59
	v_pk_add_f32 v[58:59], v[58:59], v[62:63]
	v_exp_f32_e32 v37, v55
	v_mov_b32_e32 v57, v59
	v_add_f32_e32 v55, v58, v59
	v_pk_add_f32 v[56:57], v[56:57], v[60:61]
	v_exp_f32_e32 v58, v55
	v_add_f32_e32 v55, v56, v57
	v_exp_f32_e32 v56, v55
	v_add_f32_e32 v55, v60, v57
	v_add_f32_e32 v57, v34, v55
	v_pk_add_f32 v[54:55], v[54:55], v[64:65]
	v_cndmask_b32_e64 v59, 0, v37, s[34:35]
	v_add_f32_e32 v37, v64, v55
	v_add_f32_e32 v54, v54, v55
	v_fmamk_f32 v55, v35, 0x3e38aa3b, v53
	v_pk_add_f32 v[52:53], v[36:37], v[52:53]
	v_add_f32_e32 v55, v55, v37
	v_add_f32_e32 v52, v52, v53
	v_add_f32_e32 v53, v111, v113
	v_add_f32_e32 v50, v50, v53
	v_exp_f32_e32 v51, v51
	v_exp_f32_e32 v57, v57
	v_exp_f32_e32 v54, v54
	v_exp_f32_e32 v55, v55
	v_exp_f32_e32 v52, v52
	v_exp_f32_e32 v50, v50
	v_cndmask_b32_e64 v51, 0, v51, s[12:13]
	v_cndmask_b32_e64 v58, 0, v58, s[30:31]
	v_cndmask_b32_e64 v56, 0, v56, s[28:29]
	v_cndmask_b32_e64 v57, 0, v57, s[20:21]
	v_cndmask_b32_e64 v53, 0, v54, s[18:19]
	v_cndmask_b32_e64 v54, 0, v55, s[14:15]
	v_cndmask_b32_e64 v52, 0, v52, s[10:11]
	v_cndmask_b32_e32 v50, 0, v50, vcc
	v_add_f32_e32 v55, v106, v120
	v_add_f32_e32 v129, v129, v55
	v_cvt_pk_bf16_f32 v118, v52, v54
	v_cvt_pk_bf16_f32 v119, v53, v57
	v_cvt_pk_bf16_f32 v120, v56, v58
	v_cvt_pk_bf16_f32 v121, v59, v107
	v_cvt_pk_bf16_f32 v110, v45, v44
	v_cvt_pk_bf16_f32 v111, v43, v48
	v_cvt_pk_bf16_f32 v112, v47, v46
	v_cvt_pk_bf16_f32 v113, v42, v151
	v_cvt_pk_bf16_f32 v114, v50, v51
	v_cvt_pk_bf16_f32 v115, v38, v117
	v_cvt_pk_bf16_f32 v116, v40, v137
	v_cvt_pk_bf16_f32 v117, v128, v41
	v_cvt_pk_bf16_f32 v106, v49, v148
	v_readlane_b32 s58, v255, 22
	v_readlane_b32 s73, v255, 21
	v_readlane_b32 s59, v255, 23
	s_mov_b32 s86, 0x800000
	s_movk_i32 s62, 0x1ff
	s_movk_i32 s87, 0x1600
	v_cvt_pk_bf16_f32 v107, v150, v154
	v_cvt_pk_bf16_f32 v108, v153, v159
	v_cvt_pk_bf16_f32 v109, v158, v156

; #define LAS __attribute__((address_space(3)))
; #define PVS(s, pk) do { const bf16x8 a0_ = *(const LAS bf16x8*)(vb + (s) * 32), a1_ = *(const LAS bf16x8*)(vb + 32 * VT_STRIDE + (s) * 32); \
;             o0 = __builtin_amdgcn_mfma_f32_32x32x16_bf16(a0_, pk, o0, 0, 0, 0); o1 = __builtin_amdgcn_mfma_f32_32x32x16_bf16(a1_, pk, o1, 0, 0, 0); } while (0)
; #define PVS(s, pk) do { const bf16x8 a0_ = *(const LAS bf16x8*)(vb + (s) * 32), a1_ = *(const LAS bf16x8*)(vb + 32 * VT_STRIDE + (s) * 32); \
;             o0 = __builtin_amdgcn_mfma_f32_32x32x16_bf16(a0_, pk, o0, 0, 0, 0); o1 = __builtin_amdgcn_mfma_f32_32x32x16_bf16(a1_, pk, o1, 0, 0, 0); } while (0)
; #define PVS(s, pk) do { const bf16x8 a0_ = *(const LAS bf16x8*)(vb + (s) * 32), a1_ = *(const LAS bf16x8*)(vb + 32 * VT_STRIDE + (s) * 32); \
;             o0 = __builtin_amdgcn_mfma_f32_32x32x16_bf16(a0_, pk, o0, 0, 0, 0); o1 = __builtin_amdgcn_mfma_f32_32x32x16_bf16(a1_, pk, o1, 0, 0, 0); } while (0)
; #define PVS(s, pk) do { const bf16x8 a0_ = *(const LAS bf16x8*)(vb + (s) * 32), a1_ = *(const LAS bf16x8*)(vb + 32 * VT_STRIDE + (s) * 32); \
;             o0 = __builtin_amdgcn_mfma_f32_32x32x16_bf16(a0_, pk, o0, 0, 0, 0); o1 = __builtin_amdgcn_mfma_f32_32x32x16_bf16(a1_, pk, o1, 0, 0, 0); } while (0)
; #define PVS(s, pk) do { const bf16x8 a0_ = *(const LAS bf16x8*)(vb + (s) * 32), a1_ = *(const LAS bf16x8*)(vb + 32 * VT_STRIDE + (s) * 32); \
;             o0 = __builtin_amdgcn_mfma_f32_32x32x16_bf16(a0_, pk, o0, 0, 0, 0); o1 = __builtin_amdgcn_mfma_f32_32x32x16_bf16(a1_, pk, o1, 0, 0, 0); } while (0)
; template <int MODE>
; __device__ __forceinline__ void attn_unit(LAS unsigned char* lds, const AttnArgs& A, int qb) {
;     ...
;         if (MODE == M_SB || MODE == M_FOX) {
;             const LAS unsigned* vv = (const LAS unsigned*)(lds + VOTE_OFF) + (i & 1) * 8;
;             const unsigned all8 = (vv[0] & vv[1]) & (vv[2] & vv[3]) & (vv[4] & vv[5]) & (vv[6] & vv[7]);
;             if (all8) break;
;         }
;         }
;     }
;     ...
;     if (prev_active) {
;         const LAS unsigned char* vb = lds + prevbuf + KB_BYTES + r32 * VT_STRIDE + hi * 16;
;     ...
;         PVS(0, pkP0); PVS(1, pkP1); PVS(2, pkP2); PVS(3, pkP3);
;     ...
;     }
.LBB0_1218:
	s_mov_b64 s[12:13], s[92:93]
	s_and_b64 vcc, exec, s[10:11]
	s_cbranch_vccnz .Lsb_exit_o
.LBB0_1219:
	s_mov_b32 s0, s80
	s_cmp_ge_u32 s0, s2
	s_mov_b64 s[10:11], -1
	s_cbranch_scc0 .LBB0_1166
.Lsb_exit_o:
	v_mov_b64_e32 v[64:65], v[16:17]
	v_mov_b64_e32 v[48:49], v[32:33]
	v_mov_b64_e32 v[62:63], v[14:15]
	v_mov_b64_e32 v[60:61], v[12:13]
	v_mov_b64_e32 v[58:59], v[10:11]
	v_mov_b64_e32 v[56:57], v[8:9]
	v_mov_b64_e32 v[54:55], v[6:7]
	v_mov_b64_e32 v[52:53], v[4:5]
	v_mov_b64_e32 v[50:51], v[2:3]
	v_mov_b64_e32 v[46:47], v[30:31]
	v_mov_b64_e32 v[44:45], v[28:29]
	v_mov_b64_e32 v[42:43], v[26:27]
	v_mov_b64_e32 v[40:41], v[24:25]
	v_mov_b64_e32 v[38:39], v[22:23]
	v_mov_b64_e32 v[36:37], v[20:21]
	v_mov_b64_e32 v[34:35], v[18:19]
.LBB0_1220:
	s_waitcnt vmcnt(0)
	s_andn2_b64 vcc, exec, s[12:13]
	s_cbranch_vccnz .LBB0_1155
	s_add_i32 s0, s16, 0
	v_add3_u32 v6, s0, v132, v122
	ds_read_b128 v[2:5], v6 offset:8192
	s_waitcnt lgkmcnt(0)
	v_mfma_f32_32x32x16_bf16 v[50:65], v[2:5], v[118:121], v[50:65]
	ds_read_b128 v[2:5], v6 offset:12800
	s_waitcnt lgkmcnt(0)
	v_mfma_f32_32x32x16_bf16 v[34:49], v[2:5], v[118:121], v[34:49]
	ds_read_b128 v[2:5], v6 offset:8224
	s_waitcnt lgkmcnt(0)
	v_mfma_f32_32x32x16_bf16 v[50:65], v[2:5], v[110:113], v[50:65]
	ds_read_b128 v[2:5], v6 offset:12832
	s_waitcnt lgkmcnt(0)
	v_mfma_f32_32x32x16_bf16 v[34:49], v[2:5], v[110:113], v[34:49]
	ds_read_b128 v[2:5], v6 offset:8256
	s_waitcnt lgkmcnt(0)
	v_mfma_f32_32x32x16_bf16 v[50:65], v[2:5], v[114:117], v[50:65]
	ds_read_b128 v[2:5], v6 offset:12864
	s_waitcnt lgkmcnt(0)
	v_mfma_f32_32x32x16_bf16 v[34:49], v[2:5], v[114:117], v[34:49]
	ds_read_b128 v[2:5], v6 offset:8288
	s_waitcnt lgkmcnt(0)
	v_mfma_f32_32x32x16_bf16 v[50:65], v[2:5], v[106:109], v[50:65]
	ds_read_b128 v[2:5], v6 offset:12896
	s_waitcnt lgkmcnt(0)
	v_mfma_f32_32x32x16_bf16 v[34:49], v[2:5], v[106:109], v[34:49]
	s_branch .LBB0_1155
